# NA tile: only the PV operand read-ahead (original rescale placement)
# speedup vs baseline: 1.0012x; 1.0012x over previous
; #define SBAR() __builtin_amdgcn_sched_barrier(0)
; __device__ __forceinline__ int crow(int r, int hi) { return (r & 3) + 8 * (r >> 2) + 4 * hi; }
; template <int KS> __device__ __forceinline__ void pv_step(f32x16* o, int vb, bf16x8 pa) {
;   const s16x4 l0 = tr_read<v_rd_off(0, KS, 0)>(vb), h0 = tr_read<v_rd_off(0, KS, 1)>(vb), l1 = tr_read<v_rd_off(1, KS, 0)>(vb), h1 = tr_read<v_rd_off(1, KS, 1)>(vb);
;   const s16x4 l2 = tr_read<v_rd_off(2, KS, 0)>(vb), h2 = tr_read<v_rd_off(2, KS, 1)>(vb), l3 = tr_read<v_rd_off(3, KS, 0)>(vb), h3 = tr_read<v_rd_off(3, KS, 1)>(vb);
;   asm volatile("s_waitcnt lgkmcnt(0)" ::: "memory"); SBAR();
;     ...
;   o[0] = __builtin_amdgcn_mfma_f32_32x32x16_bf16(pa, PK(l0, h0), o[0], 0, 0, 0);
;   o[1] = __builtin_amdgcn_mfma_f32_32x32x16_bf16(pa, PK(l1, h1), o[1], 0, 0, 0);
;   o[2] = __builtin_amdgcn_mfma_f32_32x32x16_bf16(pa, PK(l2, h2), o[2], 0, 0, 0);
;   o[3] = __builtin_amdgcn_mfma_f32_32x32x16_bf16(pa, PK(l3, h3), o[3], 0, 0, 0);
;     ...
; }
; template <bool DIFF> ...
;     ...
;         const float mn = fmaxf(m1, mx), alpha = __builtin_amdgcn_exp2f((m1 - mn) * C), x1 = -mn * C; m1 = mn;
;         float ps = 0.f;
; #pragma unroll
;         for (int r = 0; r < 16; ++r) { a0[r] = __builtin_amdgcn_exp2f(fmaf(a0[r], C, x1)); ps += a0[r]; }
; #pragma unroll
;         for (int r = 0; r < 16; ++r) { a1[r] = __builtin_amdgcn_exp2f(fmaf(a1[r], C, x1)); ps += a1[r]; }
;         l1 = l1 * alpha + ps;
;         if (__any(alpha < 1.0f)) {
;           if (hi == 0) wsc[r32] = alpha;
;           asm volatile("s_waitcnt lgkmcnt(0)" ::: "memory");
; #pragma unroll
;           for (int r = 0; r < 16; ++r) { const float al = wsc[crow(r, hi)];
; #pragma unroll
;             for (int d = 0; d < 4; ++d) o[d][r] *= al; }
;         }
;         PK4(a0, 0, pa0); PK4(a0, 8, pa1); PK4(a1, 0, pa2); PK4(a1, 8, pa3);
;         SBAR();
;         pv_step<0>(o, vb0, pa0); pv_step<1>(o, vb0, pa1); pv_step<2>(o, vb0, pa2); pv_step<3>(o, vb0, pa3);
.LBB0_438:
	ds_read_b64_tr_b16 v[210:211], v158 offset:0x1000
	ds_read_b64_tr_b16 v[212:213], v158 offset:0x1800
	ds_read_b64_tr_b16 v[214:215], v158 offset:0x1200
	ds_read_b64_tr_b16 v[216:217], v158 offset:0x1a00
	ds_read_b64_tr_b16 v[218:219], v158 offset:0x1400
	ds_read_b64_tr_b16 v[220:221], v158 offset:0x1c00
	ds_read_b64_tr_b16 v[222:223], v158 offset:0x1600
	ds_read_b64_tr_b16 v[224:225], v158 offset:0x1e00
	ds_read_b64_tr_b16 v[234:235], v158 offset:0x2000
	ds_read_b64_tr_b16 v[236:237], v158 offset:0x2800
	ds_read_b64_tr_b16 v[238:239], v158 offset:0x2200
	ds_read_b64_tr_b16 v[240:241], v158 offset:0x2a00
	ds_read_b64_tr_b16 v[242:243], v158 offset:0x2400
	ds_read_b64_tr_b16 v[244:245], v158 offset:0x2c00
	ds_read_b64_tr_b16 v[246:247], v158 offset:0x2600
	ds_read_b64_tr_b16 v[248:249], v158 offset:0x2e00
	v_mul_f32_e32 v81, 0xbe0293ee, v68
	v_fmamk_f32 v83, v185, 0x3e0293ee, v81
	v_exp_f32_e32 v83, v83
	v_fmamk_f32 v84, v153, 0x3e0293ee, v81
	v_exp_f32_e32 v84, v84
	v_fmamk_f32 v85, v99, 0x3e0293ee, v81
	v_exp_f32_e32 v85, v85
	v_fmamk_f32 v86, v98, 0x3e0293ee, v81
	v_exp_f32_e32 v86, v86
	v_fmamk_f32 v88, v101, 0x3e0293ee, v81
	v_add_f32_e32 v87, 0, v83
	v_exp_f32_e32 v88, v88
	v_fmamk_f32 v89, v100, 0x3e0293ee, v81
	v_add_f32_e32 v87, v84, v87
	v_exp_f32_e32 v89, v89
	v_fmamk_f32 v90, v103, 0x3e0293ee, v81
	v_add_f32_e32 v87, v85, v87
	v_exp_f32_e32 v90, v90
	v_fmamk_f32 v91, v102, 0x3e0293ee, v81
	v_add_f32_e32 v87, v86, v87
	v_exp_f32_e32 v91, v91
	v_fmamk_f32 v92, v105, 0x3e0293ee, v81
	v_add_f32_e32 v87, v88, v87
	v_exp_f32_e32 v92, v92
	v_fmamk_f32 v93, v104, 0x3e0293ee, v81
	v_add_f32_e32 v87, v89, v87
	v_exp_f32_e32 v93, v93
	v_fmamk_f32 v94, v107, 0x3e0293ee, v81
	v_add_f32_e32 v87, v90, v87
	v_exp_f32_e32 v94, v94
	v_fmamk_f32 v95, v106, 0x3e0293ee, v81
	v_add_f32_e32 v87, v91, v87
	v_exp_f32_e32 v95, v95
	v_fmamk_f32 v96, v109, 0x3e0293ee, v81
	v_add_f32_e32 v87, v92, v87
	v_exp_f32_e32 v96, v96
	v_fmamk_f32 v97, v108, 0x3e0293ee, v81
	v_add_f32_e32 v87, v93, v87
	v_exp_f32_e32 v97, v97
	v_fmamk_f32 v98, v111, 0x3e0293ee, v81
	v_add_f32_e32 v87, v94, v87
	v_exp_f32_e32 v98, v98
	v_fmamk_f32 v99, v110, 0x3e0293ee, v81
	v_add_f32_e32 v87, v95, v87
	v_exp_f32_e32 v99, v99
	v_fmamk_f32 v100, v113, 0x3e0293ee, v81
	v_add_f32_e32 v87, v96, v87
	v_exp_f32_e32 v100, v100
	v_fmamk_f32 v101, v112, 0x3e0293ee, v81
	v_add_f32_e32 v87, v97, v87
	v_exp_f32_e32 v101, v101
	v_fmamk_f32 v67, v67, 0x3e0293ee, v81
	v_add_f32_e32 v87, v98, v87
	v_exp_f32_e32 v67, v67
	v_fmamk_f32 v66, v66, 0x3e0293ee, v81
	v_add_f32_e32 v87, v99, v87
	v_exp_f32_e32 v66, v66
	v_fmamk_f32 v82, v82, 0x3e0293ee, v81
	v_add_f32_e32 v87, v100, v87
	v_exp_f32_e32 v82, v82
	v_fmamk_f32 v69, v69, 0x3e0293ee, v81
	v_add_f32_e32 v87, v101, v87
	v_exp_f32_e32 v69, v69
	v_fmamk_f32 v71, v71, 0x3e0293ee, v81
	v_add_f32_e32 v87, v67, v87
	v_exp_f32_e32 v102, v71
	v_fmamk_f32 v70, v70, 0x3e0293ee, v81
	v_add_f32_e32 v87, v66, v87
	v_exp_f32_e32 v103, v70
	v_fmamk_f32 v71, v73, 0x3e0293ee, v81
	v_add_f32_e32 v70, v82, v87
	v_exp_f32_e32 v87, v71
	v_fmamk_f32 v71, v72, 0x3e0293ee, v81
	v_add_f32_e32 v70, v69, v70
	v_exp_f32_e32 v104, v71
	v_fmamk_f32 v71, v75, 0x3e0293ee, v81
	v_add_f32_e32 v70, v102, v70
	v_exp_f32_e32 v105, v71
	v_fmamk_f32 v71, v74, 0x3e0293ee, v81
	v_add_f32_e32 v70, v103, v70
	v_exp_f32_e32 v106, v71
	v_fmamk_f32 v71, v77, 0x3e0293ee, v81
	v_add_f32_e32 v70, v87, v70
	v_exp_f32_e32 v107, v71
	v_fmamk_f32 v71, v76, 0x3e0293ee, v81
	v_add_f32_e32 v70, v104, v70
	v_exp_f32_e32 v108, v71
	v_fmamk_f32 v71, v79, 0x3e0293ee, v81
	v_add_f32_e32 v70, v105, v70
	v_exp_f32_e32 v109, v71
	v_fmac_f32_e32 v81, 0x3e0293ee, v78
	v_add_f32_e32 v70, v106, v70
	v_exp_f32_e32 v110, v81
	v_add_f32_e32 v70, v107, v70
	v_add_f32_e32 v70, v108, v70
	v_add_f32_e32 v70, v109, v70
	v_add_f32_e32 v111, v110, v70
	v_fmac_f32_e32 v111, v183, v80
	v_cvt_pk_bf16_f32 v70, v83, v84
	v_cvt_pk_bf16_f32 v71, v85, v86
	v_cvt_pk_bf16_f32 v72, v88, v89
	v_cvt_pk_bf16_f32 v73, v90, v91
	v_cvt_pk_bf16_f32 v74, v92, v93
	v_cvt_pk_bf16_f32 v75, v94, v95
	v_cvt_pk_bf16_f32 v76, v96, v97
	v_cvt_pk_bf16_f32 v77, v98, v99
	v_cvt_pk_bf16_f32 v78, v100, v101
	v_cvt_pk_bf16_f32 v79, v67, v66
	v_cvt_pk_bf16_f32 v80, v82, v69
	v_cvt_pk_bf16_f32 v81, v102, v103
	v_cvt_pk_bf16_f32 v82, v87, v104
	ds_read_b64_tr_b16 v[86:87], v158 offset:0
	ds_read_b64_tr_b16 v[88:89], v158 offset:0x800
	ds_read_b64_tr_b16 v[90:91], v158 offset:0x200
	ds_read_b64_tr_b16 v[92:93], v158 offset:0xa00
	ds_read_b64_tr_b16 v[94:95], v158 offset:0x400
	ds_read_b64_tr_b16 v[96:97], v158 offset:0xc00
	ds_read_b64_tr_b16 v[98:99], v158 offset:0x600
	ds_read_b64_tr_b16 v[100:101], v158 offset:0xe00
	v_cvt_pk_bf16_f32 v83, v105, v106
	v_cvt_pk_bf16_f32 v84, v107, v108
	v_cvt_pk_bf16_f32 v85, v109, v110
	v_permlane32_swap_b32_e32 v70, v72
	v_permlane32_swap_b32_e32 v71, v73
	v_permlane32_swap_b32_e32 v74, v76
	v_permlane32_swap_b32_e32 v75, v77
	v_permlane32_swap_b32_e32 v78, v80
	v_permlane32_swap_b32_e32 v79, v81
	v_permlane32_swap_b32_e32 v82, v84
	v_permlane32_swap_b32_e32 v83, v85
	ds_read_b64_tr_b16 v[114:115], v158 offset:0x3000
	ds_read_b64_tr_b16 v[116:117], v158 offset:0x3800
	ds_read_b64_tr_b16 v[118:119], v158 offset:0x3200
	ds_read_b64_tr_b16 v[120:121], v158 offset:0x3a00
	ds_read_b64_tr_b16 v[122:123], v158 offset:0x3400
	ds_read_b64_tr_b16 v[124:125], v158 offset:0x3c00
	ds_read_b64_tr_b16 v[126:127], v158 offset:0x3600
	ds_read_b64_tr_b16 v[128:129], v158 offset:0x3e00
	s_waitcnt lgkmcnt(8)
	v_mfma_f32_32x32x16_bf16 v[50:65], v[70:73], v[86:89], v[50:65]
	v_mfma_f32_32x32x16_bf16 v[34:49], v[70:73], v[90:93], v[34:49]
	v_mfma_f32_32x32x16_bf16 v[18:33], v[70:73], v[94:97], v[18:33]
	v_mfma_f32_32x32x16_bf16 v[2:17], v[70:73], v[98:101], v[2:17]
	v_mfma_f32_32x32x16_bf16 v[50:65], v[74:77], v[210:213], v[50:65]
	v_mfma_f32_32x32x16_bf16 v[34:49], v[74:77], v[214:217], v[34:49]
	v_mfma_f32_32x32x16_bf16 v[18:33], v[74:77], v[218:221], v[18:33]
	v_mfma_f32_32x32x16_bf16 v[2:17], v[74:77], v[222:225], v[2:17]
	v_mfma_f32_32x32x16_bf16 v[50:65], v[78:81], v[234:237], v[50:65]
	v_mfma_f32_32x32x16_bf16 v[34:49], v[78:81], v[238:241], v[34:49]
	v_mfma_f32_32x32x16_bf16 v[18:33], v[78:81], v[242:245], v[18:33]
	v_mfma_f32_32x32x16_bf16 v[2:17], v[78:81], v[246:249], v[2:17]
	s_waitcnt lgkmcnt(0)
	v_mfma_f32_32x32x16_bf16 v[50:65], v[82:85], v[114:117], v[50:65]
	v_mov_b32_e32 v184, v68
	v_mov_b32_e32 v183, v111
	v_mfma_f32_32x32x16_bf16 v[34:49], v[82:85], v[118:121], v[34:49]
	v_mfma_f32_32x32x16_bf16 v[18:33], v[82:85], v[122:125], v[18:33]
	v_mfma_f32_32x32x16_bf16 v[2:17], v[82:85], v[126:129], v[2:17]
